# GEMM3 fused epilogue: conv3 + bias + silu*v on channel pairs with packed f32 math (v_pk_fma_f32 / v_pk_mul_f32), tokens 2,3 before tokens 0,1
# speedup vs baseline: 1.0220x; 1.0036x over previous
; __device__ __forceinline__ float siluf_(float x) { return x * __builtin_amdgcn_rcpf(1.f + __expf(-x)); }
; template <int NT, bool SAMPLE>
; __device__ __forceinline__ void ffn_item(const bf16_t* U, int row0, bool has_hist, const float* st, int cgi, const float* w, const float* bias, bf16_t* ACT, float* state_out) {
;     ...
;     for (int t = 0; t < NT; ++t) {
;         float cg_[8], cv_[8], o[8];
;         unpack8(rg[t], cg_); unpack8(rv[t], cv_);
; #pragma unroll
;         for (int e = 0; e < 8; ++e) {
;             const float gg = g0[e] * wg[0][e] + g1[e] * wg[1][e] + cg_[e] * wg[2][e] + bg[e];
;             const float vv = v0[e] * wv[0][e] + v1[e] * wv[1][e] + cv_[e] * wv[2][e] + bvv[e];
;             o[e] = siluf_(gg) * vv; g0[e] = g1[e]; g1[e] = cg_[e]; v0[e] = v1[e]; v1[e] = cv_[e]; }
;         *(u32x4*)(ACT + (size_t)(row0 + t) * FF + c0) = pack8(o);
.Lepi7_nostate3:
	s_waitcnt vmcnt(16)
	v_mov_b32_e32 v137, 0xbfb8aa3b
	v_mov_b32_e32 v213, 1.0
	v_mov_b32_dpp v244, v92 row_shr:1 row_mask:0xf bank_mask:0xf
	v_mov_b32_dpp v245, v93 row_shr:1 row_mask:0xf bank_mask:0xf
	v_mov_b32_dpp v246, v76 row_shr:1 row_mask:0xf bank_mask:0xf
	v_mov_b32_dpp v247, v77 row_shr:1 row_mask:0xf bank_mask:0xf
	v_mov_b32_dpp v248, v84 row_shr:1 row_mask:0xf bank_mask:0xf
	v_mov_b32_dpp v249, v85 row_shr:1 row_mask:0xf bank_mask:0xf
	v_mov_b32_dpp v250, v68 row_shr:1 row_mask:0xf bank_mask:0xf
	v_mov_b32_dpp v251, v69 row_shr:1 row_mask:0xf bank_mask:0xf
	v_pk_fma_f32 v[144:145], v[92:93], v[208:209], v[228:229]
	v_pk_fma_f32 v[214:215], v[84:85], v[220:221], v[236:237]
	v_pk_fma_f32 v[166:167], v[76:77], v[208:209], v[228:229]
	v_pk_fma_f32 v[168:169], v[68:69], v[220:221], v[236:237]
	v_pk_fma_f32 v[144:145], v[108:109], v[192:193], v[144:145]
	v_pk_fma_f32 v[214:215], v[100:101], v[200:201], v[214:215]
	v_pk_fma_f32 v[166:167], v[92:93], v[192:193], v[166:167]
	v_pk_fma_f32 v[168:169], v[84:85], v[200:201], v[168:169]
	v_pk_fma_f32 v[144:145], v[124:125], v[176:177], v[144:145]
	v_pk_fma_f32 v[214:215], v[116:117], v[184:185], v[214:215]
	v_pk_fma_f32 v[166:167], v[108:109], v[176:177], v[166:167]
	v_pk_fma_f32 v[168:169], v[100:101], v[184:185], v[168:169]
	v_pk_mul_f32 v[170:171], v[144:145], v[136:137] op_sel:[0,1] op_sel_hi:[1,1]
	v_pk_mul_f32 v[172:173], v[166:167], v[136:137] op_sel:[0,1] op_sel_hi:[1,1]
	v_exp_f32_e32 v170, v170
	v_exp_f32_e32 v171, v171
	v_exp_f32_e32 v172, v172
	v_exp_f32_e32 v173, v173
	v_pk_add_f32 v[170:171], v[170:171], v[212:213] op_sel:[0,1] op_sel_hi:[1,1]
	v_pk_add_f32 v[172:173], v[172:173], v[212:213] op_sel:[0,1] op_sel_hi:[1,1]
	v_rcp_f32_e32 v170, v170
	v_rcp_f32_e32 v171, v171
	v_rcp_f32_e32 v172, v172
	v_rcp_f32_e32 v173, v173
	v_pk_mul_f32 v[144:145], v[144:145], v[214:215]
	v_pk_mul_f32 v[166:167], v[166:167], v[168:169]
	v_pk_mul_f32 v[92:93], v[144:145], v[170:171]
	v_pk_mul_f32 v[76:77], v[166:167], v[172:173]
	v_pk_fma_f32 v[144:145], v[124:125], v[208:209], v[228:229]
	v_pk_fma_f32 v[214:215], v[116:117], v[220:221], v[236:237]
	v_pk_fma_f32 v[166:167], v[108:109], v[208:209], v[228:229]
	v_pk_fma_f32 v[168:169], v[100:101], v[220:221], v[236:237]
	v_pk_fma_f32 v[144:145], v[246:247], v[192:193], v[144:145]
	v_pk_fma_f32 v[214:215], v[250:251], v[200:201], v[214:215]
	v_pk_fma_f32 v[166:167], v[124:125], v[192:193], v[166:167]
	v_pk_fma_f32 v[168:169], v[116:117], v[200:201], v[168:169]
	v_pk_fma_f32 v[144:145], v[244:245], v[176:177], v[144:145]
	v_pk_fma_f32 v[214:215], v[248:249], v[184:185], v[214:215]
	v_pk_fma_f32 v[166:167], v[246:247], v[176:177], v[166:167]
	v_pk_fma_f32 v[168:169], v[250:251], v[184:185], v[168:169]
	v_pk_mul_f32 v[170:171], v[144:145], v[136:137] op_sel:[0,1] op_sel_hi:[1,1]
	v_pk_mul_f32 v[172:173], v[166:167], v[136:137] op_sel:[0,1] op_sel_hi:[1,1]
	v_exp_f32_e32 v170, v170
	v_exp_f32_e32 v171, v171
	v_exp_f32_e32 v172, v172
	v_exp_f32_e32 v173, v173
	v_pk_add_f32 v[170:171], v[170:171], v[212:213] op_sel:[0,1] op_sel_hi:[1,1]
	v_pk_add_f32 v[172:173], v[172:173], v[212:213] op_sel:[0,1] op_sel_hi:[1,1]
	v_rcp_f32_e32 v170, v170
	v_rcp_f32_e32 v171, v171
	v_rcp_f32_e32 v172, v172
	v_rcp_f32_e32 v173, v173
	v_pk_mul_f32 v[144:145], v[144:145], v[214:215]
	v_pk_mul_f32 v[166:167], v[166:167], v[168:169]
	v_pk_mul_f32 v[124:125], v[144:145], v[170:171]
	v_pk_mul_f32 v[108:109], v[166:167], v[172:173]
	v_mov_b32_dpp v244, v94 row_shr:1 row_mask:0xf bank_mask:0xf
	v_mov_b32_dpp v245, v95 row_shr:1 row_mask:0xf bank_mask:0xf
	v_mov_b32_dpp v246, v78 row_shr:1 row_mask:0xf bank_mask:0xf
	v_mov_b32_dpp v247, v79 row_shr:1 row_mask:0xf bank_mask:0xf
	v_mov_b32_dpp v248, v86 row_shr:1 row_mask:0xf bank_mask:0xf
	v_mov_b32_dpp v249, v87 row_shr:1 row_mask:0xf bank_mask:0xf
	v_mov_b32_dpp v250, v70 row_shr:1 row_mask:0xf bank_mask:0xf
	v_mov_b32_dpp v251, v71 row_shr:1 row_mask:0xf bank_mask:0xf
	v_pk_fma_f32 v[144:145], v[94:95], v[210:211], v[230:231]
	v_pk_fma_f32 v[214:215], v[86:87], v[222:223], v[238:239]
	v_pk_fma_f32 v[166:167], v[78:79], v[210:211], v[230:231]
	v_pk_fma_f32 v[168:169], v[70:71], v[222:223], v[238:239]
	v_pk_fma_f32 v[144:145], v[110:111], v[194:195], v[144:145]
	v_pk_fma_f32 v[214:215], v[102:103], v[202:203], v[214:215]
	v_pk_fma_f32 v[166:167], v[94:95], v[194:195], v[166:167]
	v_pk_fma_f32 v[168:169], v[86:87], v[202:203], v[168:169]
	v_pk_fma_f32 v[144:145], v[126:127], v[178:179], v[144:145]
	v_pk_fma_f32 v[214:215], v[118:119], v[186:187], v[214:215]
	v_pk_fma_f32 v[166:167], v[110:111], v[178:179], v[166:167]
	v_pk_fma_f32 v[168:169], v[102:103], v[186:187], v[168:169]
	v_pk_mul_f32 v[170:171], v[144:145], v[136:137] op_sel:[0,1] op_sel_hi:[1,1]
	v_pk_mul_f32 v[172:173], v[166:167], v[136:137] op_sel:[0,1] op_sel_hi:[1,1]
	v_exp_f32_e32 v170, v170
	v_exp_f32_e32 v171, v171
	v_exp_f32_e32 v172, v172
	v_exp_f32_e32 v173, v173
	v_pk_add_f32 v[170:171], v[170:171], v[212:213] op_sel:[0,1] op_sel_hi:[1,1]
	v_pk_add_f32 v[172:173], v[172:173], v[212:213] op_sel:[0,1] op_sel_hi:[1,1]
	v_rcp_f32_e32 v170, v170
	v_rcp_f32_e32 v171, v171
	v_rcp_f32_e32 v172, v172
	v_rcp_f32_e32 v173, v173
	v_pk_mul_f32 v[144:145], v[144:145], v[214:215]
	v_pk_mul_f32 v[166:167], v[166:167], v[168:169]
	v_pk_mul_f32 v[94:95], v[144:145], v[170:171]
	v_pk_mul_f32 v[78:79], v[166:167], v[172:173]
	v_pk_fma_f32 v[144:145], v[126:127], v[210:211], v[230:231]
	v_pk_fma_f32 v[214:215], v[118:119], v[222:223], v[238:239]
	v_pk_fma_f32 v[166:167], v[110:111], v[210:211], v[230:231]
	v_pk_fma_f32 v[168:169], v[102:103], v[222:223], v[238:239]
; __device__ __forceinline__ float siluf_(float x) { return x * __builtin_amdgcn_rcpf(1.f + __expf(-x)); }
; template <int NT, bool SAMPLE>
; __device__ __forceinline__ void ffn_item(const bf16_t* U, int row0, bool has_hist, const float* st, int cgi, const float* w, const float* bias, bf16_t* ACT, float* state_out) {
;     ...
; #pragma unroll
;     for (int t = 0; t < NT; ++t) {
;         float cg_[8], cv_[8], o[8];
;         unpack8(rg[t], cg_); unpack8(rv[t], cv_);
; #pragma unroll
;         for (int e = 0; e < 8; ++e) {
;             const float gg = g0[e] * wg[0][e] + g1[e] * wg[1][e] + cg_[e] * wg[2][e] + bg[e];
;             const float vv = v0[e] * wv[0][e] + v1[e] * wv[1][e] + cv_[e] * wv[2][e] + bvv[e];
;             o[e] = siluf_(gg) * vv; g0[e] = g1[e]; g1[e] = cg_[e]; v0[e] = v1[e]; v1[e] = cv_[e]; }
;         *(u32x4*)(ACT + (size_t)(row0 + t) * FF + c0) = pack8(o);
;     }
	v_pk_fma_f32 v[144:145], v[246:247], v[194:195], v[144:145]
	v_pk_fma_f32 v[214:215], v[250:251], v[202:203], v[214:215]
	v_pk_fma_f32 v[166:167], v[126:127], v[194:195], v[166:167]
	v_pk_fma_f32 v[168:169], v[118:119], v[202:203], v[168:169]
	v_pk_fma_f32 v[144:145], v[244:245], v[178:179], v[144:145]
	v_pk_fma_f32 v[214:215], v[248:249], v[186:187], v[214:215]
	v_pk_fma_f32 v[166:167], v[246:247], v[178:179], v[166:167]
	v_pk_fma_f32 v[168:169], v[250:251], v[186:187], v[168:169]
	v_pk_mul_f32 v[170:171], v[144:145], v[136:137] op_sel:[0,1] op_sel_hi:[1,1]
	v_pk_mul_f32 v[172:173], v[166:167], v[136:137] op_sel:[0,1] op_sel_hi:[1,1]
	v_exp_f32_e32 v170, v170
	v_exp_f32_e32 v171, v171
	v_exp_f32_e32 v172, v172
	v_exp_f32_e32 v173, v173
	v_pk_add_f32 v[170:171], v[170:171], v[212:213] op_sel:[0,1] op_sel_hi:[1,1]
	v_pk_add_f32 v[172:173], v[172:173], v[212:213] op_sel:[0,1] op_sel_hi:[1,1]
	v_rcp_f32_e32 v170, v170
	v_rcp_f32_e32 v171, v171
	v_rcp_f32_e32 v172, v172
	v_rcp_f32_e32 v173, v173
	v_pk_mul_f32 v[144:145], v[144:145], v[214:215]
	v_pk_mul_f32 v[166:167], v[166:167], v[168:169]
	v_pk_mul_f32 v[126:127], v[144:145], v[170:171]
	v_pk_mul_f32 v[110:111], v[166:167], v[172:173]
	v_mov_b32_dpp v244, v88 row_shr:1 row_mask:0xf bank_mask:0xf
	v_mov_b32_dpp v245, v89 row_shr:1 row_mask:0xf bank_mask:0xf
	v_mov_b32_dpp v246, v72 row_shr:1 row_mask:0xf bank_mask:0xf
	v_mov_b32_dpp v247, v73 row_shr:1 row_mask:0xf bank_mask:0xf
	v_mov_b32_dpp v248, v80 row_shr:1 row_mask:0xf bank_mask:0xf
	v_mov_b32_dpp v249, v81 row_shr:1 row_mask:0xf bank_mask:0xf
	v_mov_b32_dpp v250, v64 row_shr:1 row_mask:0xf bank_mask:0xf
	v_mov_b32_dpp v251, v65 row_shr:1 row_mask:0xf bank_mask:0xf
	v_pk_fma_f32 v[144:145], v[88:89], v[216:217], v[232:233]
	v_pk_fma_f32 v[214:215], v[80:81], v[224:225], v[240:241]
	v_pk_fma_f32 v[166:167], v[72:73], v[216:217], v[232:233]
	v_pk_fma_f32 v[168:169], v[64:65], v[224:225], v[240:241]
	v_pk_fma_f32 v[144:145], v[104:105], v[196:197], v[144:145]
	v_pk_fma_f32 v[214:215], v[96:97], v[204:205], v[214:215]
	v_pk_fma_f32 v[166:167], v[88:89], v[196:197], v[166:167]
	v_pk_fma_f32 v[168:169], v[80:81], v[204:205], v[168:169]
	v_pk_fma_f32 v[144:145], v[120:121], v[180:181], v[144:145]
	v_pk_fma_f32 v[214:215], v[112:113], v[188:189], v[214:215]
	v_pk_fma_f32 v[166:167], v[104:105], v[180:181], v[166:167]
	v_pk_fma_f32 v[168:169], v[96:97], v[188:189], v[168:169]
	v_pk_mul_f32 v[170:171], v[144:145], v[136:137] op_sel:[0,1] op_sel_hi:[1,1]
	v_pk_mul_f32 v[172:173], v[166:167], v[136:137] op_sel:[0,1] op_sel_hi:[1,1]
	v_exp_f32_e32 v170, v170
	v_exp_f32_e32 v171, v171
	v_exp_f32_e32 v172, v172
	v_exp_f32_e32 v173, v173
	v_pk_add_f32 v[170:171], v[170:171], v[212:213] op_sel:[0,1] op_sel_hi:[1,1]
	v_pk_add_f32 v[172:173], v[172:173], v[212:213] op_sel:[0,1] op_sel_hi:[1,1]
	v_rcp_f32_e32 v170, v170
	v_rcp_f32_e32 v171, v171
	v_rcp_f32_e32 v172, v172
	v_rcp_f32_e32 v173, v173
	v_pk_mul_f32 v[144:145], v[144:145], v[214:215]
	v_pk_mul_f32 v[166:167], v[166:167], v[168:169]
	v_pk_mul_f32 v[88:89], v[144:145], v[170:171]
	v_pk_mul_f32 v[72:73], v[166:167], v[172:173]
	v_pk_fma_f32 v[144:145], v[120:121], v[216:217], v[232:233]
	v_pk_fma_f32 v[214:215], v[112:113], v[224:225], v[240:241]
	v_pk_fma_f32 v[166:167], v[104:105], v[216:217], v[232:233]
	v_pk_fma_f32 v[168:169], v[96:97], v[224:225], v[240:241]
	v_pk_fma_f32 v[144:145], v[246:247], v[196:197], v[144:145]
	v_pk_fma_f32 v[214:215], v[250:251], v[204:205], v[214:215]
	v_pk_fma_f32 v[166:167], v[120:121], v[196:197], v[166:167]
	v_pk_fma_f32 v[168:169], v[112:113], v[204:205], v[168:169]
	v_pk_fma_f32 v[144:145], v[244:245], v[180:181], v[144:145]
	v_pk_fma_f32 v[214:215], v[248:249], v[188:189], v[214:215]
	v_pk_fma_f32 v[166:167], v[246:247], v[180:181], v[166:167]
	v_pk_fma_f32 v[168:169], v[250:251], v[188:189], v[168:169]
	v_pk_mul_f32 v[170:171], v[144:145], v[136:137] op_sel:[0,1] op_sel_hi:[1,1]
	v_pk_mul_f32 v[172:173], v[166:167], v[136:137] op_sel:[0,1] op_sel_hi:[1,1]
	v_exp_f32_e32 v170, v170
	v_exp_f32_e32 v171, v171
	v_exp_f32_e32 v172, v172
	v_exp_f32_e32 v173, v173
	v_pk_add_f32 v[170:171], v[170:171], v[212:213] op_sel:[0,1] op_sel_hi:[1,1]
	v_pk_add_f32 v[172:173], v[172:173], v[212:213] op_sel:[0,1] op_sel_hi:[1,1]
	v_rcp_f32_e32 v170, v170
	v_rcp_f32_e32 v171, v171
	v_rcp_f32_e32 v172, v172
	v_rcp_f32_e32 v173, v173
	v_pk_mul_f32 v[144:145], v[144:145], v[214:215]
	v_pk_mul_f32 v[166:167], v[166:167], v[168:169]
	v_pk_mul_f32 v[120:121], v[144:145], v[170:171]
	v_pk_mul_f32 v[104:105], v[166:167], v[172:173]
	v_mov_b32_dpp v244, v90 row_shr:1 row_mask:0xf bank_mask:0xf
	v_mov_b32_dpp v245, v91 row_shr:1 row_mask:0xf bank_mask:0xf
	v_mov_b32_dpp v246, v74 row_shr:1 row_mask:0xf bank_mask:0xf
	v_mov_b32_dpp v247, v75 row_shr:1 row_mask:0xf bank_mask:0xf
	v_mov_b32_dpp v248, v82 row_shr:1 row_mask:0xf bank_mask:0xf
	v_mov_b32_dpp v249, v83 row_shr:1 row_mask:0xf bank_mask:0xf
	v_mov_b32_dpp v250, v66 row_shr:1 row_mask:0xf bank_mask:0xf
	v_mov_b32_dpp v251, v67 row_shr:1 row_mask:0xf bank_mask:0xf
	v_pk_fma_f32 v[144:145], v[90:91], v[218:219], v[234:235]
	v_pk_fma_f32 v[214:215], v[82:83], v[226:227], v[242:243]
	v_pk_fma_f32 v[166:167], v[74:75], v[218:219], v[234:235]
	v_pk_fma_f32 v[168:169], v[66:67], v[226:227], v[242:243]
	v_pk_fma_f32 v[144:145], v[106:107], v[198:199], v[144:145]
	v_pk_fma_f32 v[214:215], v[98:99], v[206:207], v[214:215]
	v_pk_fma_f32 v[166:167], v[90:91], v[198:199], v[166:167]
	v_pk_fma_f32 v[168:169], v[82:83], v[206:207], v[168:169]
	v_pk_fma_f32 v[144:145], v[122:123], v[182:183], v[144:145]
	v_pk_fma_f32 v[214:215], v[114:115], v[190:191], v[214:215]
; __device__ __forceinline__ float siluf_(float x) { return x * __builtin_amdgcn_rcpf(1.f + __expf(-x)); }
; template <int NT, bool SAMPLE>
; __device__ __forceinline__ void ffn_item(const bf16_t* U, int row0, bool has_hist, const float* st, int cgi, const float* w, const float* bias, bf16_t* ACT, float* state_out) {
;     ...
; #pragma unroll
;     for (int t = 0; t < NT; ++t) {
;         float cg_[8], cv_[8], o[8];
;         unpack8(rg[t], cg_); unpack8(rv[t], cv_);
; #pragma unroll
;         for (int e = 0; e < 8; ++e) {
;             const float gg = g0[e] * wg[0][e] + g1[e] * wg[1][e] + cg_[e] * wg[2][e] + bg[e];
;             const float vv = v0[e] * wv[0][e] + v1[e] * wv[1][e] + cv_[e] * wv[2][e] + bvv[e];
;             o[e] = siluf_(gg) * vv; g0[e] = g1[e]; g1[e] = cg_[e]; v0[e] = v1[e]; v1[e] = cv_[e]; }
;         *(u32x4*)(ACT + (size_t)(row0 + t) * FF + c0) = pack8(o);
;     }
	v_pk_fma_f32 v[166:167], v[106:107], v[182:183], v[166:167]
	v_pk_fma_f32 v[168:169], v[98:99], v[190:191], v[168:169]
	v_pk_mul_f32 v[170:171], v[144:145], v[136:137] op_sel:[0,1] op_sel_hi:[1,1]
	v_pk_mul_f32 v[172:173], v[166:167], v[136:137] op_sel:[0,1] op_sel_hi:[1,1]
	v_exp_f32_e32 v170, v170
	v_exp_f32_e32 v171, v171
	v_exp_f32_e32 v172, v172
	v_exp_f32_e32 v173, v173
	v_pk_add_f32 v[170:171], v[170:171], v[212:213] op_sel:[0,1] op_sel_hi:[1,1]
	v_pk_add_f32 v[172:173], v[172:173], v[212:213] op_sel:[0,1] op_sel_hi:[1,1]
	v_rcp_f32_e32 v170, v170
	v_rcp_f32_e32 v171, v171
	v_rcp_f32_e32 v172, v172
	v_rcp_f32_e32 v173, v173
	v_pk_mul_f32 v[144:145], v[144:145], v[214:215]
	v_pk_mul_f32 v[166:167], v[166:167], v[168:169]
	v_pk_mul_f32 v[90:91], v[144:145], v[170:171]
	v_pk_mul_f32 v[74:75], v[166:167], v[172:173]
	v_pk_fma_f32 v[144:145], v[122:123], v[218:219], v[234:235]
	v_pk_fma_f32 v[214:215], v[114:115], v[226:227], v[242:243]
	v_pk_fma_f32 v[166:167], v[106:107], v[218:219], v[234:235]
	v_pk_fma_f32 v[168:169], v[98:99], v[226:227], v[242:243]
	v_pk_fma_f32 v[144:145], v[246:247], v[198:199], v[144:145]
	v_pk_fma_f32 v[214:215], v[250:251], v[206:207], v[214:215]
	v_pk_fma_f32 v[166:167], v[122:123], v[198:199], v[166:167]
	v_pk_fma_f32 v[168:169], v[114:115], v[206:207], v[168:169]
	v_pk_fma_f32 v[144:145], v[244:245], v[182:183], v[144:145]
	v_pk_fma_f32 v[214:215], v[248:249], v[190:191], v[214:215]
	v_pk_fma_f32 v[166:167], v[246:247], v[182:183], v[166:167]
	v_pk_fma_f32 v[168:169], v[250:251], v[190:191], v[168:169]
	v_pk_mul_f32 v[170:171], v[144:145], v[136:137] op_sel:[0,1] op_sel_hi:[1,1]
	v_pk_mul_f32 v[172:173], v[166:167], v[136:137] op_sel:[0,1] op_sel_hi:[1,1]
	v_exp_f32_e32 v170, v170
	v_exp_f32_e32 v171, v171
	v_exp_f32_e32 v172, v172
	v_exp_f32_e32 v173, v173
	v_pk_add_f32 v[170:171], v[170:171], v[212:213] op_sel:[0,1] op_sel_hi:[1,1]
	v_pk_add_f32 v[172:173], v[172:173], v[212:213] op_sel:[0,1] op_sel_hi:[1,1]
	v_rcp_f32_e32 v170, v170
	v_rcp_f32_e32 v171, v171
	v_rcp_f32_e32 v172, v172
	v_rcp_f32_e32 v173, v173
	v_pk_mul_f32 v[144:145], v[144:145], v[214:215]
	v_pk_mul_f32 v[166:167], v[166:167], v[168:169]
	v_pk_mul_f32 v[122:123], v[144:145], v[170:171]
	v_pk_mul_f32 v[106:107], v[166:167], v[172:173]
	v_mov_b32_dpp v244, v28 row_shr:1 row_mask:0xf bank_mask:0xf
	v_mov_b32_dpp v245, v29 row_shr:1 row_mask:0xf bank_mask:0xf
	v_mov_b32_dpp v246, v12 row_shr:1 row_mask:0xf bank_mask:0xf
	v_mov_b32_dpp v247, v13 row_shr:1 row_mask:0xf bank_mask:0xf
	v_mov_b32_dpp v248, v20 row_shr:1 row_mask:0xf bank_mask:0xf
	v_mov_b32_dpp v249, v21 row_shr:1 row_mask:0xf bank_mask:0xf
	v_mov_b32_dpp v250, v4 row_shr:1 row_mask:0xf bank_mask:0xf
	v_mov_b32_dpp v251, v5 row_shr:1 row_mask:0xf bank_mask:0xf
	v_pk_fma_f32 v[144:145], v[28:29], v[208:209], v[228:229]
	v_pk_fma_f32 v[214:215], v[20:21], v[220:221], v[236:237]
	v_pk_fma_f32 v[166:167], v[12:13], v[208:209], v[228:229]
	v_pk_fma_f32 v[168:169], v[4:5], v[220:221], v[236:237]
	v_pk_fma_f32 v[144:145], v[44:45], v[192:193], v[144:145]
	v_pk_fma_f32 v[214:215], v[36:37], v[200:201], v[214:215]
	v_pk_fma_f32 v[166:167], v[28:29], v[192:193], v[166:167]
	v_pk_fma_f32 v[168:169], v[20:21], v[200:201], v[168:169]
	v_pk_fma_f32 v[144:145], v[60:61], v[176:177], v[144:145]
	v_pk_fma_f32 v[214:215], v[52:53], v[184:185], v[214:215]
	v_pk_fma_f32 v[166:167], v[44:45], v[176:177], v[166:167]
	v_pk_fma_f32 v[168:169], v[36:37], v[184:185], v[168:169]
	v_pk_mul_f32 v[170:171], v[144:145], v[136:137] op_sel:[0,1] op_sel_hi:[1,1]
	v_pk_mul_f32 v[172:173], v[166:167], v[136:137] op_sel:[0,1] op_sel_hi:[1,1]
	v_exp_f32_e32 v170, v170
	v_exp_f32_e32 v171, v171
	v_exp_f32_e32 v172, v172
	v_exp_f32_e32 v173, v173
	v_pk_add_f32 v[170:171], v[170:171], v[212:213] op_sel:[0,1] op_sel_hi:[1,1]
	v_pk_add_f32 v[172:173], v[172:173], v[212:213] op_sel:[0,1] op_sel_hi:[1,1]
	v_rcp_f32_e32 v170, v170
	v_rcp_f32_e32 v171, v171
	v_rcp_f32_e32 v172, v172
	v_rcp_f32_e32 v173, v173
	v_pk_mul_f32 v[144:145], v[144:145], v[214:215]
	v_pk_mul_f32 v[166:167], v[166:167], v[168:169]
	v_pk_mul_f32 v[28:29], v[144:145], v[170:171]
	v_pk_mul_f32 v[12:13], v[166:167], v[172:173]
	v_pk_fma_f32 v[144:145], v[60:61], v[208:209], v[228:229]
	v_pk_fma_f32 v[214:215], v[52:53], v[220:221], v[236:237]
	v_pk_fma_f32 v[166:167], v[44:45], v[208:209], v[228:229]
	v_pk_fma_f32 v[168:169], v[36:37], v[220:221], v[236:237]
	v_pk_fma_f32 v[144:145], v[246:247], v[192:193], v[144:145]
	v_pk_fma_f32 v[214:215], v[250:251], v[200:201], v[214:215]
	v_pk_fma_f32 v[166:167], v[60:61], v[192:193], v[166:167]
	v_pk_fma_f32 v[168:169], v[52:53], v[200:201], v[168:169]
	v_pk_fma_f32 v[144:145], v[244:245], v[176:177], v[144:145]
	v_pk_fma_f32 v[214:215], v[248:249], v[184:185], v[214:215]
	v_pk_fma_f32 v[166:167], v[246:247], v[176:177], v[166:167]
	v_pk_fma_f32 v[168:169], v[250:251], v[184:185], v[168:169]
	v_pk_mul_f32 v[170:171], v[144:145], v[136:137] op_sel:[0,1] op_sel_hi:[1,1]
	v_pk_mul_f32 v[172:173], v[166:167], v[136:137] op_sel:[0,1] op_sel_hi:[1,1]
	v_exp_f32_e32 v170, v170
	v_exp_f32_e32 v171, v171
	v_exp_f32_e32 v172, v172
	v_exp_f32_e32 v173, v173
	v_pk_add_f32 v[170:171], v[170:171], v[212:213] op_sel:[0,1] op_sel_hi:[1,1]
	v_pk_add_f32 v[172:173], v[172:173], v[212:213] op_sel:[0,1] op_sel_hi:[1,1]
	v_rcp_f32_e32 v170, v170
	v_rcp_f32_e32 v171, v171
	v_rcp_f32_e32 v172, v172
	v_rcp_f32_e32 v173, v173
	v_pk_mul_f32 v[144:145], v[144:145], v[214:215]
	v_pk_mul_f32 v[166:167], v[166:167], v[168:169]
	v_pk_mul_f32 v[60:61], v[144:145], v[170:171]
	v_pk_mul_f32 v[44:45], v[166:167], v[172:173]
; __device__ __forceinline__ float siluf_(float x) { return x * __builtin_amdgcn_rcpf(1.f + __expf(-x)); }
; template <int NT, bool SAMPLE>
; __device__ __forceinline__ void ffn_item(const bf16_t* U, int row0, bool has_hist, const float* st, int cgi, const float* w, const float* bias, bf16_t* ACT, float* state_out) {
;     ...
; #pragma unroll
;     for (int t = 0; t < NT; ++t) {
;         float cg_[8], cv_[8], o[8];
;         unpack8(rg[t], cg_); unpack8(rv[t], cv_);
; #pragma unroll
;         for (int e = 0; e < 8; ++e) {
;             const float gg = g0[e] * wg[0][e] + g1[e] * wg[1][e] + cg_[e] * wg[2][e] + bg[e];
;             const float vv = v0[e] * wv[0][e] + v1[e] * wv[1][e] + cv_[e] * wv[2][e] + bvv[e];
;             o[e] = siluf_(gg) * vv; g0[e] = g1[e]; g1[e] = cg_[e]; v0[e] = v1[e]; v1[e] = cv_[e]; }
;         *(u32x4*)(ACT + (size_t)(row0 + t) * FF + c0) = pack8(o);
;     }
	v_mov_b32_dpp v244, v30 row_shr:1 row_mask:0xf bank_mask:0xf
	v_mov_b32_dpp v245, v31 row_shr:1 row_mask:0xf bank_mask:0xf
	v_mov_b32_dpp v246, v14 row_shr:1 row_mask:0xf bank_mask:0xf
	v_mov_b32_dpp v247, v15 row_shr:1 row_mask:0xf bank_mask:0xf
	v_mov_b32_dpp v248, v22 row_shr:1 row_mask:0xf bank_mask:0xf
	v_mov_b32_dpp v249, v23 row_shr:1 row_mask:0xf bank_mask:0xf
	v_mov_b32_dpp v250, v6 row_shr:1 row_mask:0xf bank_mask:0xf
	v_mov_b32_dpp v251, v7 row_shr:1 row_mask:0xf bank_mask:0xf
	v_pk_fma_f32 v[144:145], v[30:31], v[210:211], v[230:231]
	v_pk_fma_f32 v[214:215], v[22:23], v[222:223], v[238:239]
	v_pk_fma_f32 v[166:167], v[14:15], v[210:211], v[230:231]
	v_pk_fma_f32 v[168:169], v[6:7], v[222:223], v[238:239]
	v_pk_fma_f32 v[144:145], v[46:47], v[194:195], v[144:145]
	v_pk_fma_f32 v[214:215], v[38:39], v[202:203], v[214:215]
	v_pk_fma_f32 v[166:167], v[30:31], v[194:195], v[166:167]
	v_pk_fma_f32 v[168:169], v[22:23], v[202:203], v[168:169]
	v_pk_fma_f32 v[144:145], v[62:63], v[178:179], v[144:145]
	v_pk_fma_f32 v[214:215], v[54:55], v[186:187], v[214:215]
	v_pk_fma_f32 v[166:167], v[46:47], v[178:179], v[166:167]
	v_pk_fma_f32 v[168:169], v[38:39], v[186:187], v[168:169]
	v_pk_mul_f32 v[170:171], v[144:145], v[136:137] op_sel:[0,1] op_sel_hi:[1,1]
	v_pk_mul_f32 v[172:173], v[166:167], v[136:137] op_sel:[0,1] op_sel_hi:[1,1]
	v_exp_f32_e32 v170, v170
	v_exp_f32_e32 v171, v171
	v_exp_f32_e32 v172, v172
	v_exp_f32_e32 v173, v173
	v_pk_add_f32 v[170:171], v[170:171], v[212:213] op_sel:[0,1] op_sel_hi:[1,1]
	v_pk_add_f32 v[172:173], v[172:173], v[212:213] op_sel:[0,1] op_sel_hi:[1,1]
	v_rcp_f32_e32 v170, v170
	v_rcp_f32_e32 v171, v171
	v_rcp_f32_e32 v172, v172
	v_rcp_f32_e32 v173, v173
	v_pk_mul_f32 v[144:145], v[144:145], v[214:215]
	v_pk_mul_f32 v[166:167], v[166:167], v[168:169]
	v_pk_mul_f32 v[30:31], v[144:145], v[170:171]
	v_pk_mul_f32 v[14:15], v[166:167], v[172:173]
	v_pk_fma_f32 v[144:145], v[62:63], v[210:211], v[230:231]
	v_pk_fma_f32 v[214:215], v[54:55], v[222:223], v[238:239]
	v_pk_fma_f32 v[166:167], v[46:47], v[210:211], v[230:231]
	v_pk_fma_f32 v[168:169], v[38:39], v[222:223], v[238:239]
	v_pk_fma_f32 v[144:145], v[246:247], v[194:195], v[144:145]
	v_pk_fma_f32 v[214:215], v[250:251], v[202:203], v[214:215]
	v_pk_fma_f32 v[166:167], v[62:63], v[194:195], v[166:167]
	v_pk_fma_f32 v[168:169], v[54:55], v[202:203], v[168:169]
	v_pk_fma_f32 v[144:145], v[244:245], v[178:179], v[144:145]
	v_pk_fma_f32 v[214:215], v[248:249], v[186:187], v[214:215]
	v_pk_fma_f32 v[166:167], v[246:247], v[178:179], v[166:167]
	v_pk_fma_f32 v[168:169], v[250:251], v[186:187], v[168:169]
	v_pk_mul_f32 v[170:171], v[144:145], v[136:137] op_sel:[0,1] op_sel_hi:[1,1]
	v_pk_mul_f32 v[172:173], v[166:167], v[136:137] op_sel:[0,1] op_sel_hi:[1,1]
	v_exp_f32_e32 v170, v170
	v_exp_f32_e32 v171, v171
	v_exp_f32_e32 v172, v172
	v_exp_f32_e32 v173, v173
	v_pk_add_f32 v[170:171], v[170:171], v[212:213] op_sel:[0,1] op_sel_hi:[1,1]
	v_pk_add_f32 v[172:173], v[172:173], v[212:213] op_sel:[0,1] op_sel_hi:[1,1]
	v_rcp_f32_e32 v170, v170
	v_rcp_f32_e32 v171, v171
	v_rcp_f32_e32 v172, v172
	v_rcp_f32_e32 v173, v173
	v_pk_mul_f32 v[144:145], v[144:145], v[214:215]
	v_pk_mul_f32 v[166:167], v[166:167], v[168:169]
	v_pk_mul_f32 v[62:63], v[144:145], v[170:171]
	v_pk_mul_f32 v[46:47], v[166:167], v[172:173]
	v_mov_b32_dpp v244, v24 row_shr:1 row_mask:0xf bank_mask:0xf
	v_mov_b32_dpp v245, v25 row_shr:1 row_mask:0xf bank_mask:0xf
	v_mov_b32_dpp v246, v8 row_shr:1 row_mask:0xf bank_mask:0xf
	v_mov_b32_dpp v247, v9 row_shr:1 row_mask:0xf bank_mask:0xf
	v_mov_b32_dpp v248, v16 row_shr:1 row_mask:0xf bank_mask:0xf
	v_mov_b32_dpp v249, v17 row_shr:1 row_mask:0xf bank_mask:0xf
	v_mov_b32_dpp v250, v0 row_shr:1 row_mask:0xf bank_mask:0xf
	v_mov_b32_dpp v251, v1 row_shr:1 row_mask:0xf bank_mask:0xf
	v_pk_fma_f32 v[144:145], v[24:25], v[216:217], v[232:233]
	v_pk_fma_f32 v[214:215], v[16:17], v[224:225], v[240:241]
	v_pk_fma_f32 v[166:167], v[8:9], v[216:217], v[232:233]
	v_pk_fma_f32 v[168:169], v[0:1], v[224:225], v[240:241]
	v_pk_fma_f32 v[144:145], v[40:41], v[196:197], v[144:145]
	v_pk_fma_f32 v[214:215], v[32:33], v[204:205], v[214:215]
	v_pk_fma_f32 v[166:167], v[24:25], v[196:197], v[166:167]
	v_pk_fma_f32 v[168:169], v[16:17], v[204:205], v[168:169]
	v_pk_fma_f32 v[144:145], v[56:57], v[180:181], v[144:145]
	v_pk_fma_f32 v[214:215], v[48:49], v[188:189], v[214:215]
	v_pk_fma_f32 v[166:167], v[40:41], v[180:181], v[166:167]
	v_pk_fma_f32 v[168:169], v[32:33], v[188:189], v[168:169]
	v_pk_mul_f32 v[170:171], v[144:145], v[136:137] op_sel:[0,1] op_sel_hi:[1,1]
	v_pk_mul_f32 v[172:173], v[166:167], v[136:137] op_sel:[0,1] op_sel_hi:[1,1]
	v_exp_f32_e32 v170, v170
	v_exp_f32_e32 v171, v171
	v_exp_f32_e32 v172, v172
	v_exp_f32_e32 v173, v173
	v_pk_add_f32 v[170:171], v[170:171], v[212:213] op_sel:[0,1] op_sel_hi:[1,1]
	v_pk_add_f32 v[172:173], v[172:173], v[212:213] op_sel:[0,1] op_sel_hi:[1,1]
	v_rcp_f32_e32 v170, v170
	v_rcp_f32_e32 v171, v171
	v_rcp_f32_e32 v172, v172
	v_rcp_f32_e32 v173, v173
	v_pk_mul_f32 v[144:145], v[144:145], v[214:215]
	v_pk_mul_f32 v[166:167], v[166:167], v[168:169]
	v_pk_mul_f32 v[24:25], v[144:145], v[170:171]
	v_pk_mul_f32 v[8:9], v[166:167], v[172:173]
	v_pk_fma_f32 v[144:145], v[56:57], v[216:217], v[232:233]
	v_pk_fma_f32 v[214:215], v[48:49], v[224:225], v[240:241]
	v_pk_fma_f32 v[166:167], v[40:41], v[216:217], v[232:233]
	v_pk_fma_f32 v[168:169], v[32:33], v[224:225], v[240:241]
	v_pk_fma_f32 v[144:145], v[246:247], v[196:197], v[144:145]
	v_pk_fma_f32 v[214:215], v[250:251], v[204:205], v[214:215]
	v_pk_fma_f32 v[166:167], v[56:57], v[196:197], v[166:167]
; __device__ __forceinline__ float siluf_(float x) { return x * __builtin_amdgcn_rcpf(1.f + __expf(-x)); }
; template <int NT, bool SAMPLE>
; __device__ __forceinline__ void ffn_item(const bf16_t* U, int row0, bool has_hist, const float* st, int cgi, const float* w, const float* bias, bf16_t* ACT, float* state_out) {
;     ...
; #pragma unroll
;     for (int t = 0; t < NT; ++t) {
;         float cg_[8], cv_[8], o[8];
;         unpack8(rg[t], cg_); unpack8(rv[t], cv_);
; #pragma unroll
;         for (int e = 0; e < 8; ++e) {
;             const float gg = g0[e] * wg[0][e] + g1[e] * wg[1][e] + cg_[e] * wg[2][e] + bg[e];
;             const float vv = v0[e] * wv[0][e] + v1[e] * wv[1][e] + cv_[e] * wv[2][e] + bvv[e];
;             o[e] = siluf_(gg) * vv; g0[e] = g1[e]; g1[e] = cg_[e]; v0[e] = v1[e]; v1[e] = cv_[e]; }
;         *(u32x4*)(ACT + (size_t)(row0 + t) * FF + c0) = pack8(o);
;     }
	v_pk_fma_f32 v[168:169], v[48:49], v[204:205], v[168:169]
	v_pk_fma_f32 v[144:145], v[244:245], v[180:181], v[144:145]
	v_pk_fma_f32 v[214:215], v[248:249], v[188:189], v[214:215]
	v_pk_fma_f32 v[166:167], v[246:247], v[180:181], v[166:167]
	v_pk_fma_f32 v[168:169], v[250:251], v[188:189], v[168:169]
	v_pk_mul_f32 v[170:171], v[144:145], v[136:137] op_sel:[0,1] op_sel_hi:[1,1]
	v_pk_mul_f32 v[172:173], v[166:167], v[136:137] op_sel:[0,1] op_sel_hi:[1,1]
	v_exp_f32_e32 v170, v170
	v_exp_f32_e32 v171, v171
	v_exp_f32_e32 v172, v172
	v_exp_f32_e32 v173, v173
	v_pk_add_f32 v[170:171], v[170:171], v[212:213] op_sel:[0,1] op_sel_hi:[1,1]
	v_pk_add_f32 v[172:173], v[172:173], v[212:213] op_sel:[0,1] op_sel_hi:[1,1]
	v_rcp_f32_e32 v170, v170
	v_rcp_f32_e32 v171, v171
	v_rcp_f32_e32 v172, v172
	v_rcp_f32_e32 v173, v173
	v_pk_mul_f32 v[144:145], v[144:145], v[214:215]
	v_pk_mul_f32 v[166:167], v[166:167], v[168:169]
	v_pk_mul_f32 v[56:57], v[144:145], v[170:171]
	v_pk_mul_f32 v[40:41], v[166:167], v[172:173]
	v_mov_b32_dpp v244, v26 row_shr:1 row_mask:0xf bank_mask:0xf
	v_mov_b32_dpp v245, v27 row_shr:1 row_mask:0xf bank_mask:0xf
	v_mov_b32_dpp v246, v10 row_shr:1 row_mask:0xf bank_mask:0xf
	v_mov_b32_dpp v247, v11 row_shr:1 row_mask:0xf bank_mask:0xf
	v_mov_b32_dpp v248, v18 row_shr:1 row_mask:0xf bank_mask:0xf
	v_mov_b32_dpp v249, v19 row_shr:1 row_mask:0xf bank_mask:0xf
	v_mov_b32_dpp v250, v2 row_shr:1 row_mask:0xf bank_mask:0xf
	v_mov_b32_dpp v251, v3 row_shr:1 row_mask:0xf bank_mask:0xf
	v_pk_fma_f32 v[144:145], v[26:27], v[218:219], v[234:235]
	v_pk_fma_f32 v[214:215], v[18:19], v[226:227], v[242:243]
	v_pk_fma_f32 v[166:167], v[10:11], v[218:219], v[234:235]
	v_pk_fma_f32 v[168:169], v[2:3], v[226:227], v[242:243]
	v_pk_fma_f32 v[144:145], v[42:43], v[198:199], v[144:145]
	v_pk_fma_f32 v[214:215], v[34:35], v[206:207], v[214:215]
	v_pk_fma_f32 v[166:167], v[26:27], v[198:199], v[166:167]
	v_pk_fma_f32 v[168:169], v[18:19], v[206:207], v[168:169]
	v_pk_fma_f32 v[144:145], v[58:59], v[182:183], v[144:145]
	v_pk_fma_f32 v[214:215], v[50:51], v[190:191], v[214:215]
	v_pk_fma_f32 v[166:167], v[42:43], v[182:183], v[166:167]
	v_pk_fma_f32 v[168:169], v[34:35], v[190:191], v[168:169]
	v_pk_mul_f32 v[170:171], v[144:145], v[136:137] op_sel:[0,1] op_sel_hi:[1,1]
	v_pk_mul_f32 v[172:173], v[166:167], v[136:137] op_sel:[0,1] op_sel_hi:[1,1]
	v_exp_f32_e32 v170, v170
	v_exp_f32_e32 v171, v171
	v_exp_f32_e32 v172, v172
	v_exp_f32_e32 v173, v173
	v_pk_add_f32 v[170:171], v[170:171], v[212:213] op_sel:[0,1] op_sel_hi:[1,1]
	v_pk_add_f32 v[172:173], v[172:173], v[212:213] op_sel:[0,1] op_sel_hi:[1,1]
	v_rcp_f32_e32 v170, v170
	v_rcp_f32_e32 v171, v171
	v_rcp_f32_e32 v172, v172
	v_rcp_f32_e32 v173, v173
	v_pk_mul_f32 v[144:145], v[144:145], v[214:215]
	v_pk_mul_f32 v[166:167], v[166:167], v[168:169]
	v_pk_mul_f32 v[26:27], v[144:145], v[170:171]
	v_pk_mul_f32 v[10:11], v[166:167], v[172:173]
	v_pk_fma_f32 v[144:145], v[58:59], v[218:219], v[234:235]
	v_pk_fma_f32 v[214:215], v[50:51], v[226:227], v[242:243]
	v_pk_fma_f32 v[166:167], v[42:43], v[218:219], v[234:235]
	v_pk_fma_f32 v[168:169], v[34:35], v[226:227], v[242:243]
	v_pk_fma_f32 v[144:145], v[246:247], v[198:199], v[144:145]
	v_pk_fma_f32 v[214:215], v[250:251], v[206:207], v[214:215]
	v_pk_fma_f32 v[166:167], v[58:59], v[198:199], v[166:167]
	v_pk_fma_f32 v[168:169], v[50:51], v[206:207], v[168:169]
	v_pk_fma_f32 v[144:145], v[244:245], v[182:183], v[144:145]
	v_pk_fma_f32 v[214:215], v[248:249], v[190:191], v[214:215]
	v_pk_fma_f32 v[166:167], v[246:247], v[182:183], v[166:167]
	v_pk_fma_f32 v[168:169], v[250:251], v[190:191], v[168:169]
	v_pk_mul_f32 v[170:171], v[144:145], v[136:137] op_sel:[0,1] op_sel_hi:[1,1]
	v_pk_mul_f32 v[172:173], v[166:167], v[136:137] op_sel:[0,1] op_sel_hi:[1,1]
	v_exp_f32_e32 v170, v170
	v_exp_f32_e32 v171, v171
	v_exp_f32_e32 v172, v172
	v_exp_f32_e32 v173, v173
	v_pk_add_f32 v[170:171], v[170:171], v[212:213] op_sel:[0,1] op_sel_hi:[1,1]
	v_pk_add_f32 v[172:173], v[172:173], v[212:213] op_sel:[0,1] op_sel_hi:[1,1]
	v_rcp_f32_e32 v170, v170
	v_rcp_f32_e32 v171, v171
	v_rcp_f32_e32 v172, v172
	v_rcp_f32_e32 v173, v173
	v_pk_mul_f32 v[144:145], v[144:145], v[214:215]
	v_pk_mul_f32 v[166:167], v[166:167], v[168:169]
	v_pk_mul_f32 v[58:59], v[144:145], v[170:171]
	v_pk_mul_f32 v[42:43], v[166:167], v[172:173]
	s_mov_b32 exec_lo, 0xfffefffe
	s_mov_b32 exec_hi, 0xfffefffe
	v_cvt_pk_bf16_f32 v168, v124, v125
	v_cvt_pk_bf16_f32 v169, v126, v127
	v_cvt_pk_bf16_f32 v170, v120, v121
	v_cvt_pk_bf16_f32 v171, v122, v123
	global_store_dwordx4 v136, v[168:171], s[14:15]
	s_add_u32 s14, s14, 0x2b00
	s_addc_u32 s15, s15, 0
	v_cvt_pk_bf16_f32 v172, v108, v109
	v_cvt_pk_bf16_f32 v173, v110, v111
	v_cvt_pk_bf16_f32 v174, v104, v105
	v_cvt_pk_bf16_f32 v175, v106, v107
	global_store_dwordx4 v136, v[172:175], s[14:15]
	s_add_u32 s14, s14, 0x2b00
	s_addc_u32 s15, s15, 0
	s_mov_b32 exec_lo, -1
	s_mov_b32 exec_hi, -1
	v_cvt_pk_bf16_f32 v168, v92, v93
	v_cvt_pk_bf16_f32 v169, v94, v95
	v_cvt_pk_bf16_f32 v170, v88, v89
	v_cvt_pk_bf16_f32 v171, v90, v91
	global_store_dwordx4 v136, v[168:171], s[14:15]
	s_add_u32 s14, s14, 0x2b00
	s_addc_u32 s15, s15, 0
	v_cvt_pk_bf16_f32 v172, v76, v77
	v_cvt_pk_bf16_f32 v173, v78, v79
	v_cvt_pk_bf16_f32 v174, v72, v73
	v_cvt_pk_bf16_f32 v175, v74, v75
	global_store_dwordx4 v136, v[172:175], s[14:15]
	s_add_u32 s14, s14, 0x14ff00
	s_addc_u32 s15, s15, 0
	s_mov_b32 exec_lo, 0xfffefffe
	s_mov_b32 exec_hi, 0xfffefffe
	v_cvt_pk_bf16_f32 v168, v60, v61
	v_cvt_pk_bf16_f32 v169, v62, v63
	v_cvt_pk_bf16_f32 v170, v56, v57
	v_cvt_pk_bf16_f32 v171, v58, v59
	global_store_dwordx4 v136, v[168:171], s[14:15]
	s_add_u32 s14, s14, 0x2b00
	s_addc_u32 s15, s15, 0
	v_cvt_pk_bf16_f32 v172, v44, v45
	v_cvt_pk_bf16_f32 v173, v46, v47
	v_cvt_pk_bf16_f32 v174, v40, v41
	v_cvt_pk_bf16_f32 v175, v42, v43
	global_store_dwordx4 v136, v[172:175], s[14:15]
	s_add_u32 s14, s14, 0x2b00
	s_addc_u32 s15, s15, 0
	s_mov_b32 exec_lo, -1
	s_mov_b32 exec_hi, -1
	v_cvt_pk_bf16_f32 v168, v28, v29
	v_cvt_pk_bf16_f32 v169, v30, v31
	v_cvt_pk_bf16_f32 v170, v24, v25
	v_cvt_pk_bf16_f32 v171, v26, v27
	global_store_dwordx4 v136, v[168:171], s[14:15]
	s_add_u32 s14, s14, 0x2b00
	s_addc_u32 s15, s15, 0
	v_cvt_pk_bf16_f32 v172, v12, v13
	v_cvt_pk_bf16_f32 v173, v14, v15
	v_cvt_pk_bf16_f32 v174, v8, v9
	v_cvt_pk_bf16_f32 v175, v10, v11
	global_store_dwordx4 v136, v[172:175], s[14:15]
	s_mov_b64 exec, -1
	s_branch .Lepi7_done
